# attention queue counters spread to one 64-byte line per XCD queue (were 8 counters in one line)
# baseline (speedup 1.0000x reference)
.LBB0_96:
	s_add_i32 s91, s91, 1
	s_cmp_eq_u32 s91, 8
	s_cbranch_scc1 .LBB0_245
	s_mov_b32 s40, s89
	s_mov_b32 s41, s90
	v_lshlrev_b32_e32 v1, 6, v220
	v_cmp_gt_u32_e32 vcc, 8, v220
	s_and_saveexec_b64 s[2:3], vcc
	s_cbranch_execz .Lqs_nold
	global_load_dword v0, v1, s[40:41] sc1
	s_waitcnt vmcnt(0)
	v_lshlrev_b32_e32 v1, 2, v220
	ds_write_b32 v1, v0 offset:64

.LBB0_97:
	s_add_i32 s2, s91, s53
	s_and_b32 s3, s2, 7
	s_lshl_b32 s5, s3, 6
	s_add_u32 s40, s89, s5
	s_addc_u32 s41, s90, 0
	s_mul_i32 s3, s3, 6
	s_bfe_u32 s93, s2, 0x10002
	s_and_b32 s94, s2, 3
	s_lshl_b32 s2, s2, 1
	s_or_b32 s92, s3, 0xffffff40
	s_and_b32 s95, s2, 6
	s_branch .LBB0_101
